# attention: wave 0 touches the next unit's 256 Q rows (4 dword loads into unused v255) when the next ticket arrives, so the next prologue's Q loads hit lines already in flight; on top of all24
# baseline (speedup 1.0000x reference)
; __device__ __forceinline__ int lane_id_asm() { int l; asm volatile("v_mbcnt_lo_u32_b32 %0, -1, 0\n\tv_mbcnt_hi_u32_b32 %0, -1, %0" : "=v"(l)); return l; }
; __device__ __forceinline__ int crow(int r,int hi){return (r&3)+8*(r>>2)+4*hi;}
; template<int THRL> __device__ __forceinline__ void attn_unit(int b,int h,int qb,const bf16*Q,const bf16*__restrict__ K,const bf16*__restrict__ V,bf16*O,char*shm,const int wid){
;     ...
;   {auto rr=__builtin_amdgcn_permlane32_swap(__float_as_uint(l_reg),__float_as_uint(l_reg),false,false);l_reg=__uint_as_float(rr[0])+__uint_as_float(rr[1]);}
;   if(hi==0)wsf[32+r32]=l_reg;asm volatile("s_waitcnt lgkmcnt(0)":::"memory");
;   float rli[16];
;   #pragma unroll
;   for(int r=0;r<16;++r)rli[r]=__builtin_amdgcn_rcpf(wsf[32+crow(r,hi)]);
;   bf16*Ow=O+(rowbase+q0+wid*QBLK)*PO+ocol;
;   { bf16*stg=(bf16*)(shm+LDS_OST)+wid*2048;
;     #pragma unroll
;     for(int r=0;r<16;++r){const int orow=crow(r,hi);
;       #pragma unroll
;       for(int d0=0;d0<2;++d0)stg[orow*64+d0*32+r32]=__float2bfloat16(o[d0][r]*rli[r]);}
;     asm volatile("s_waitcnt lgkmcnt(0)":::"memory");
;     #pragma unroll
;     for(int i=0;i<4;++i){const int row=i*8+(lane>>3),ch=lane&7; const u32x4 v=*(const u32x4*)(stg+row*64+ch*8); ATTN_STORE16(Ow+(long)row*PO+ch*8,v);} }
;   asm volatile("s_waitcnt lgkmcnt(0)\n\ts_barrier":::"memory");
; __global__ void __launch_bounds__(NWAVES * 64, 2) hybrid_fwd(const Args A) {
;     ...
;         for (;;) {
;             if (F.wave == 0 && lane_id_asm() == 0) misc[0] = atomicAdd(F.ctl + CW_QUEUE + 64 * rep, 1u);
;             __syncthreads(); const unsigned idx = misc[0]; __syncthreads();
;             if (idx >= 1024u) break;
;             const int qb = 15 - (int)(idx >> 6), bhv = (int)(idx & 63u);
;             attn_body::attn_unit<8>(bhv >> 4, bhv & 15, qb, Pd, Pd, Pd, (attn_body::bf16*)(F.ws + WS_O), (char*)lds, F.wave);
.Lq_skip1:
	s_waitcnt lgkmcnt(0)
	ds_read_b128 v[4:7], v2 offset:49280
	ds_read_b128 v[8:11], v2 offset:49312
	v_lshlrev_b32_e32 v50, 9, v213
	s_lshl_b64 s[6:7], s[0:1], 11
	v_readlane_b32 s8, v254, 15
	s_waitcnt lgkmcnt(1)
	v_rcp_f32_e32 v0, v4
	v_rcp_f32_e32 v3, v5
	v_rcp_f32_e32 v12, v6
	v_rcp_f32_e32 v13, v7
	s_waitcnt lgkmcnt(0)
	v_rcp_f32_e32 v14, v8
	ds_read_b128 v[4:7], v2 offset:49344
	v_rcp_f32_e32 v15, v9
	v_rcp_f32_e32 v48, v10
	v_rcp_f32_e32 v49, v11
	ds_read_b128 v[8:11], v2 offset:49376
	s_waitcnt lgkmcnt(1)
	v_rcp_f32_e32 v2, v4
	v_rcp_f32_e32 v4, v5
	v_rcp_f32_e32 v5, v6
	v_rcp_f32_e32 v6, v7
	s_waitcnt lgkmcnt(0)
	v_rcp_f32_e32 v7, v8
	v_rcp_f32_e32 v8, v9
	v_rcp_f32_e32 v9, v10
	v_rcp_f32_e32 v10, v11
	v_lshlrev_b32_e32 v11, 1, v212
	v_mul_f32_e32 v32, v32, v0
	v_mul_f32_e32 v0, v16, v0
	v_add3_u32 v11, s49, v11, v50
	v_cvt_pk_bf16_f32 v0, v0, s0
	ds_write_b16 v11, v0 offset:51264
	v_mul_f32_e32 v0, v33, v3
	v_cvt_pk_bf16_f32 v0, v0, s0
	ds_write_b16 v11, v0 offset:51328
	v_mul_f32_e32 v0, v17, v3
	v_cvt_pk_bf16_f32 v0, v0, s0
	ds_write_b16 v11, v0 offset:51392
	v_mul_f32_e32 v0, v34, v12
	v_cvt_pk_bf16_f32 v0, v0, s0
	ds_write_b16 v11, v0 offset:51456
	v_mul_f32_e32 v0, v18, v12
	v_cvt_pk_bf16_f32 v0, v0, s0
	ds_write_b16 v11, v0 offset:51520
	v_mul_f32_e32 v0, v35, v13
	v_cvt_pk_bf16_f32 v0, v0, s0
	ds_write_b16 v11, v0 offset:51584
	v_mul_f32_e32 v0, v19, v13
	v_cvt_pk_bf16_f32 v0, v0, s0
	ds_write_b16 v11, v0 offset:51648
	v_mul_f32_e32 v0, v36, v14
	v_cvt_pk_bf16_f32 v0, v0, s0
	ds_write_b16 v11, v0 offset:52224
	v_mul_f32_e32 v0, v20, v14
	v_cvt_pk_bf16_f32 v0, v0, s0
	ds_write_b16 v11, v0 offset:52288
	v_mul_f32_e32 v0, v37, v15
	v_cvt_pk_bf16_f32 v0, v0, s0
	ds_write_b16 v11, v0 offset:52352
	v_mul_f32_e32 v0, v21, v15
	v_cvt_pk_bf16_f32 v0, v0, s0
	ds_write_b16 v11, v0 offset:52416
	v_mul_f32_e32 v0, v38, v48
	v_cvt_pk_bf16_f32 v0, v0, s0
	ds_write_b16 v11, v0 offset:52480
	v_mul_f32_e32 v0, v22, v48
	v_cvt_pk_bf16_f32 v0, v0, s0
	ds_write_b16 v11, v0 offset:52544
	v_mul_f32_e32 v0, v39, v49
	v_cvt_pk_bf16_f32 v0, v0, s0
	ds_write_b16 v11, v0 offset:52608
	v_mul_f32_e32 v0, v23, v49
	v_cvt_pk_bf16_f32 v0, v0, s0
	ds_write_b16 v11, v0 offset:52672
	v_mul_f32_e32 v0, v40, v2
	v_cvt_pk_bf16_f32 v0, v0, s0
	ds_write_b16 v11, v0 offset:53248
	v_mul_f32_e32 v0, v24, v2
	v_cvt_pk_bf16_f32 v0, v0, s0
	ds_write_b16 v11, v0 offset:53312
	v_mul_f32_e32 v0, v41, v4
	v_cvt_pk_bf16_f32 v0, v0, s0
	ds_write_b16 v11, v0 offset:53376
	v_mul_f32_e32 v0, v25, v4
	v_cvt_pk_bf16_f32 v0, v0, s0
	ds_write_b16 v11, v0 offset:53440
	v_mul_f32_e32 v0, v42, v5
	v_cvt_pk_bf16_f32 v0, v0, s0
	ds_write_b16 v11, v0 offset:53504
	v_mul_f32_e32 v0, v26, v5
	v_cvt_pk_bf16_f32 v0, v0, s0
	ds_write_b16 v11, v0 offset:53568
	v_mul_f32_e32 v0, v43, v6
	v_cvt_pk_bf16_f32 v0, v0, s0
	ds_write_b16 v11, v0 offset:53632
	v_mul_f32_e32 v0, v27, v6
	v_cvt_pk_bf16_f32 v0, v0, s0
	ds_write_b16 v11, v0 offset:53696
	v_mul_f32_e32 v0, v44, v7
	v_cvt_pk_bf16_f32 v0, v0, s0
	ds_write_b16 v11, v0 offset:54272
	v_mul_f32_e32 v0, v28, v7
	v_cvt_pk_bf16_f32 v0, v0, s0
	ds_write_b16 v11, v0 offset:54336
	v_mul_f32_e32 v0, v45, v8
	v_cvt_pk_bf16_f32 v0, v0, s0
	ds_write_b16 v11, v0 offset:54400
	v_mul_f32_e32 v0, v29, v8
	v_cvt_pk_bf16_f32 v0, v0, s0
	ds_write_b16 v11, v0 offset:54464
	v_mul_f32_e32 v0, v46, v9
	v_cvt_pk_bf16_f32 v0, v0, s0
	ds_write_b16 v11, v0 offset:54528
	v_mul_f32_e32 v0, v30, v9
	v_cvt_pk_bf16_f32 v0, v0, s0
	ds_write_b16 v11, v0 offset:54592
	v_mul_f32_e32 v0, v47, v10
	v_cvt_pk_bf16_f32 v0, v0, s0
	ds_write_b16 v11, v0 offset:54656
	v_mul_f32_e32 v0, v31, v10
	v_cvt_pk_bf16_f32 v32, v32, s0
	v_cvt_pk_bf16_f32 v0, v0, s0
	v_readlane_b32 s9, v254, 16
	s_add_u32 s0, s8, s6
	ds_write_b16 v11, v0 offset:54720
	s_addc_u32 s3, s9, s7
	s_lshl_b32 s6, s54, 1
	v_lshlrev_b32_e32 v0, 1, v211
	s_add_u32 s6, s0, s6
	v_and_b32_e32 v0, 0x70, v0
	ds_write_b16 v11, v32 offset:51200
	s_addc_u32 s7, s3, 0
	v_ashrrev_i32_e32 v10, 3, v210
	v_add_u32_e32 v18, s49, v0
	s_waitcnt lgkmcnt(0)
	v_lshl_add_u64 v[12:13], s[6:7], 0, v[0:1]
	v_lshl_add_u32 v0, v10, 7, v18
	ds_read_b128 v[2:5], v0 offset:51200
	v_ashrrev_i32_e32 v11, 31, v10
	v_add_u32_e32 v16, 8, v10
	v_lshlrev_b64 v[6:7], 11, v[10:11]
	v_lshl_add_u32 v0, v16, 7, v18
	v_lshl_add_u64 v[14:15], v[12:13], 0, v[6:7]
	ds_read_b128 v[6:9], v0 offset:51200
	v_ashrrev_i32_e32 v17, 31, v16
	s_cmp_lg_u64 s[4:5], 0
	s_cbranch_scc1 .Lq_skip2
	s_waitcnt vmcnt(0)
	v_readfirstlane_b32 s98, v240
	s_cmp_gt_u32 s98, s51
	s_cbranch_scc1 .Lq_skip2
	s_bfe_u32 s88, s98, 0x20004
	s_lshl_b32 s88, s88, 12
	s_lshr_b32 s89, s98, 6
	s_lshl_b32 s89, s89, 8
	s_sub_i32 s88, s88, s89
	s_addk_i32 s88, 0xf00
	s_mul_hi_u32 s89, s88, 0xc00
	s_mul_i32 s88, s88, 0xc00
	s_lshl_b32 s90, s98, 6
	s_and_b32 s90, s90, 0x380
	s_add_u32 s88, s88, s90
	s_addc_u32 s89, s89, 0
	s_add_u32 s88, s33, s88
	s_addc_u32 s89, s42, s89
	v_mbcnt_lo_u32_b32 v241, -1, 0
	v_mbcnt_hi_u32_b32 v241, -1, v241
	v_mul_u32_u24_e32 v241, 0xc00, v241
	s_add_u32 s90, s88, 0x30000
	s_addc_u32 s91, s89, 0
	s_add_u32 s94, s88, 0x60000
	s_addc_u32 s95, s89, 0
	s_add_u32 s96, s88, 0x90000
	s_addc_u32 s97, s89, 0
	global_load_dword v255, v241, s[88:89]
	global_load_dword v255, v241, s[90:91]
	global_load_dword v255, v241, s[94:95]
	global_load_dword v255, v241, s[96:97]
